# P0 MoE weight conversion: tile pairs after a wave's first come from 32 pooled atomic counters, fetched one loop trip ahead (pipeline unbroken); induction variables derived from the next-pair index
# speedup vs baseline: 1.0484x; 1.0088x over previous
.LBB0_57:
	s_or_b64 exec, exec, s[72:73]
	s_cmpk_lg_u32 s80, 0x800
	s_cbranch_scc1 .Lp0d_nofetch
	v_readlane_b32 s42, v126, 12
	v_readlane_b32 s43, v126, 13
	v_accvgpr_read_b32 v0, a1
	s_nop 0
	v_readfirstlane_b32 s44, v0
	s_and_b32 s41, s44, 7
	s_bfe_u32 s45, s44, 0x20006
	s_lshl_b32 s45, s45, 3
	s_or_b32 s41, s41, s45
	s_lshl_b32 s41, s41, 2
	s_add_u32 s42, s42, s41
	s_addc_u32 s43, s43, 0
	s_add_u32 s42, s42, 4
	s_addc_u32 s43, s43, 0
	s_and_b32 s44, s44, 0xc7
	v_mov_b32_e32 v0, 0
	v_mov_b32_e32 v2, 1
	v_accvgpr_write_b32 a77, v2
	s_mov_b64 exec, 1
	s_nop 4
	global_atomic_add a76, v0, a77, s[42:43] sc0
	s_mov_b64 exec, -1
.Lp0d_nofetch:
	s_mov_b32 s0, 0xc000
	v_accvgpr_read_b32 v92, a1
	v_cmp_gt_i32_e32 vcc, s0, v92
	s_and_saveexec_b64 s[0:1], vcc
	s_cbranch_execz .LBB0_63
	s_movk_i32 s3, 0x7fff
	v_cmp_lt_i32_e64 s[4:5], s3, v92
	s_and_saveexec_b64 s[6:7], s[4:5]
	s_xor_b64 s[4:5], exec, s[6:7]
	s_cbranch_execz .LBB0_60
	v_add_u32_e32 v0, 0xffff8000, v92
	v_lshrrev_b32_e32 v2, 9, v0
	v_lshlrev_b32_e32 v0, 6, v92
	v_and_b32_e32 v1, 0x3c0, v0
	v_lshlrev_b32_e32 v0, 2, v92
	v_and_b32_e32 v0, 0x7c0, v0
	v_mov_b32_e32 v3, 0
	v_readlane_b32 s8, v126, 2
	v_lshrrev_b32_e32 v6, 4, v83
	v_lshlrev_b64 v[4:5], 23, v[2:3]
	v_readlane_b32 s10, v126, 4
	v_readlane_b32 s11, v126, 5
	v_or_b32_e32 v6, v0, v6
	v_lshlrev_b32_e32 v6, 12, v6
	v_lshl_add_u64 v[4:5], s[10:11], 0, v[4:5]
	v_mov_b32_e32 v7, v3
	v_lshl_add_u64 v[4:5], v[4:5], 0, v[6:7]
	v_lshlrev_b32_e32 v6, 2, v1
	v_lshl_add_u64 v[4:5], v[4:5], 0, v[6:7]
	v_lshlrev_b32_e32 v6, 4, v83
	v_and_b32_e32 v6, 0xf0, v6
	v_readlane_b32 s14, v126, 8
	v_readlane_b32 s15, v126, 9
	v_lshl_add_u64 v[6:7], v[4:5], 0, v[6:7]
	v_lshlrev_b64 v[4:5], 21, v[2:3]
	v_lshl_add_u64 v[4:5], s[14:15], 0, v[4:5]
	v_lshlrev_b32_e32 v2, 11, v1
	v_lshl_add_u64 v[2:3], v[4:5], 0, v[2:3]
	s_mov_b64 s[6:7], 0x10000000
	v_readlane_b32 s9, v126, 3
	v_readlane_b32 s12, v126, 6
	v_readlane_b32 s13, v126, 7
	v_lshl_add_u64 v[66:67], v[2:3], 0, s[6:7]

.LBB0_74:
	s_waitcnt vmcnt(39)
	v_pk_mul_f32 v[84:85], v[2:3], v[70:71] op_sel_hi:[1,0]
	ds_write2_b32 v75, v84, v85 offset1:1
	v_pk_mul_f32 v[84:85], v[4:5], v[70:71] op_sel_hi:[1,0]
	ds_write2_b32 v75, v84, v85 offset0:2 offset1:3
	s_waitcnt vmcnt(38)
	v_pk_mul_f32 v[84:85], v[6:7], v[70:71] op_sel_hi:[1,0]
	v_accvgpr_read_b32 v0, a3
	ds_write2_b32 v0, v84, v85 offset1:1
	v_pk_mul_f32 v[84:85], v[8:9], v[70:71] op_sel_hi:[1,0]
	v_accvgpr_read_b32 v0, a5
	ds_write2_b32 v0, v84, v85 offset1:1
	s_waitcnt vmcnt(37)
	v_pk_mul_f32 v[84:85], v[10:11], v[70:71] op_sel_hi:[1,0]
	v_accvgpr_read_b32 v0, a7
	ds_write2_b32 v0, v84, v85 offset1:1
	v_pk_mul_f32 v[84:85], v[12:13], v[70:71] op_sel_hi:[1,0]
	v_accvgpr_read_b32 v0, a9
	ds_write2_b32 v0, v84, v85 offset1:1
	s_waitcnt vmcnt(36)
	v_pk_mul_f32 v[84:85], v[14:15], v[70:71] op_sel_hi:[1,0]
	v_accvgpr_read_b32 v0, a10
	ds_write2_b32 v0, v84, v85 offset1:1
	v_pk_mul_f32 v[84:85], v[16:17], v[70:71] op_sel_hi:[1,0]
	v_accvgpr_read_b32 v0, a11
	ds_write2_b32 v0, v84, v85 offset1:1
	s_waitcnt vmcnt(35)
	v_pk_mul_f32 v[84:85], v[18:19], v[70:71] op_sel_hi:[1,0]
	v_accvgpr_read_b32 v0, a12
	ds_write2_b32 v0, v84, v85 offset1:1
	v_pk_mul_f32 v[84:85], v[20:21], v[70:71] op_sel_hi:[1,0]
	v_accvgpr_read_b32 v0, a13
	ds_write2_b32 v0, v84, v85 offset1:1
	s_waitcnt vmcnt(34)
	v_pk_mul_f32 v[84:85], v[22:23], v[70:71] op_sel_hi:[1,0]
	v_accvgpr_read_b32 v0, a18
	ds_write2_b32 v0, v84, v85 offset1:1
	v_pk_mul_f32 v[84:85], v[24:25], v[70:71] op_sel_hi:[1,0]
	v_accvgpr_read_b32 v0, a19
	ds_write2_b32 v0, v84, v85 offset1:1
	s_waitcnt vmcnt(33)
	v_pk_mul_f32 v[84:85], v[26:27], v[70:71] op_sel_hi:[1,0]
	v_accvgpr_read_b32 v0, a20
	ds_write2_b32 v0, v84, v85 offset1:1
	v_pk_mul_f32 v[84:85], v[28:29], v[70:71] op_sel_hi:[1,0]
	v_accvgpr_read_b32 v0, a21
	ds_write2_b32 v0, v84, v85 offset1:1
	s_waitcnt vmcnt(32)
	v_pk_mul_f32 v[84:85], v[30:31], v[70:71] op_sel_hi:[1,0]
	v_accvgpr_read_b32 v0, a22
	ds_write2_b32 v0, v84, v85 offset1:1
	v_pk_mul_f32 v[84:85], v[32:33], v[70:71] op_sel_hi:[1,0]
	v_accvgpr_read_b32 v0, a23
	ds_write2_b32 v0, v84, v85 offset1:1
	s_waitcnt vmcnt(31)
	v_pk_mul_f32 v[84:85], v[34:35], v[70:71] op_sel_hi:[1,0]
	v_accvgpr_read_b32 v0, a24
	ds_write2_b32 v0, v84, v85 offset1:1
	v_pk_mul_f32 v[84:85], v[36:37], v[70:71] op_sel_hi:[1,0]
	v_accvgpr_read_b32 v0, a25
	ds_write2_b32 v0, v84, v85 offset1:1
	s_waitcnt vmcnt(30)
	v_pk_mul_f32 v[84:85], v[38:39], v[70:71] op_sel_hi:[1,0]
	v_accvgpr_read_b32 v0, a30
	ds_write2_b32 v0, v84, v85 offset1:1
	v_pk_mul_f32 v[84:85], v[40:41], v[70:71] op_sel_hi:[1,0]
	v_accvgpr_read_b32 v0, a31
	ds_write2_b32 v0, v84, v85 offset1:1
	s_waitcnt vmcnt(29)
	v_pk_mul_f32 v[84:85], v[42:43], v[70:71] op_sel_hi:[1,0]
	v_accvgpr_read_b32 v0, a32
	ds_write2_b32 v0, v84, v85 offset1:1
	v_pk_mul_f32 v[84:85], v[44:45], v[70:71] op_sel_hi:[1,0]
	v_accvgpr_read_b32 v0, a33
	ds_write2_b32 v0, v84, v85 offset1:1
	s_waitcnt vmcnt(28)
	v_pk_mul_f32 v[84:85], v[46:47], v[70:71] op_sel_hi:[1,0]
	v_accvgpr_read_b32 v0, a34
	ds_write2_b32 v0, v84, v85 offset1:1
	v_pk_mul_f32 v[84:85], v[48:49], v[70:71] op_sel_hi:[1,0]
	v_accvgpr_read_b32 v0, a35
	ds_write2_b32 v0, v84, v85 offset1:1
	s_waitcnt vmcnt(27)
	v_pk_mul_f32 v[84:85], v[50:51], v[70:71] op_sel_hi:[1,0]
	v_accvgpr_read_b32 v0, a40
	ds_write2_b32 v0, v84, v85 offset1:1
	v_pk_mul_f32 v[84:85], v[52:53], v[70:71] op_sel_hi:[1,0]
	v_accvgpr_read_b32 v0, a41
	ds_write2_b32 v0, v84, v85 offset1:1
	s_waitcnt vmcnt(26)
	v_pk_mul_f32 v[84:85], v[54:55], v[70:71] op_sel_hi:[1,0]
	v_accvgpr_read_b32 v0, a42
	ds_write2_b32 v0, v84, v85 offset1:1
	v_pk_mul_f32 v[84:85], v[56:57], v[70:71] op_sel_hi:[1,0]
	v_accvgpr_read_b32 v0, a43
	ds_write2_b32 v0, v84, v85 offset1:1
	s_waitcnt vmcnt(25)
	v_pk_mul_f32 v[84:85], v[58:59], v[70:71] op_sel_hi:[1,0]
	v_accvgpr_read_b32 v0, a44
	ds_write2_b32 v0, v84, v85 offset1:1
	v_pk_mul_f32 v[84:85], v[60:61], v[70:71] op_sel_hi:[1,0]
	v_accvgpr_read_b32 v0, a45
	ds_write2_b32 v0, v84, v85 offset1:1
	s_waitcnt vmcnt(24)
	v_pk_mul_f32 v[84:85], v[62:63], v[70:71] op_sel_hi:[1,0]
	v_accvgpr_read_b32 v0, a50
	s_cmpk_lg_u32 s80, 0x800
	s_cbranch_scc1 .Lp0d_static
	v_accvgpr_read_b32 v91, a76
	s_nop 0
	v_readfirstlane_b32 s41, v91
	s_and_b32 s45, s41, 7
	s_lshl_b32 s45, s45, 3
	s_or_b32 s45, s45, s44
	s_bfe_u32 s36, s41, 0x30003
	s_lshl_b32 s36, s36, 8
	s_or_b32 s45, s45, s36
	s_lshr_b32 s41, s41, 6
	s_add_i32 s41, s41, 1
	s_lshl_b32 s41, s41, 12
	s_add_i32 s41, s41, s45
	s_cmpk_gt_u32 s39, 0x40
	s_cselect_b32 s41, 0xc000, s41
	v_mov_b32_e32 v91, s41
	s_mov_b64 exec, 1
	s_nop 0
	global_atomic_add a76, v1, a77, s[42:43] sc0
	s_mov_b64 exec, -1
	s_branch .Lp0d_join
.Lp0d_static:
	v_add_u32_e32 v91, s3, v92
.Lp0d_join:
	ds_write2_b32 v0, v84, v85 offset1:1
	v_pk_mul_f32 v[84:85], v[64:65], v[70:71] op_sel_hi:[1,0]
	v_accvgpr_read_b32 v0, a51
	v_cmp_gt_i32_e64 s[4:5], s19, v91
	v_cmp_lt_i32_e32 vcc, s20, v91
	ds_write2_b32 v0, v84, v85 offset1:1
	s_and_saveexec_b64 s[0:1], s[4:5]
	s_cselect_b32 s38, 0, 1
	s_cbranch_execz .LBB0_80
	v_cmp_lt_i32_e64 s[4:5], s21, v91
	s_and_saveexec_b64 s[12:13], s[4:5]
	s_xor_b64 s[4:5], exec, s[12:13]
	s_cbranch_execz .LBB0_77
	v_lshlrev_b32_e32 v2, 6, v91
	v_add_u32_e32 v0, 0xffff8000, v91
	v_and_b32_e32 v6, 0x3c0, v2
	v_lshlrev_b32_e32 v2, 2, v91
	v_lshrrev_b32_e32 v0, 9, v0
	v_and_b32_e32 v82, 0x7c0, v2
	v_readlane_b32 s24, v126, 2
	v_accvgpr_read_b32 v4, a1
	v_lshlrev_b64 v[2:3], 23, v[0:1]
	v_readlane_b32 s26, v126, 4
	v_readlane_b32 s27, v126, 5
	v_or_b32_e32 v4, v82, v4
	v_lshlrev_b32_e32 v4, 12, v4
	v_lshl_add_u64 v[2:3], s[26:27], 0, v[2:3]
	v_mov_b32_e32 v5, v1
	v_lshl_add_u64 v[2:3], v[2:3], 0, v[4:5]
	v_lshlrev_b32_e32 v4, 2, v6
	v_lshl_add_u64 v[2:3], v[2:3], 0, v[4:5]
	v_lshlrev_b64 v[4:5], 21, v[0:1]
	v_lshl_add_u64 v[4:5], s[8:9], 0, v[4:5]
	v_lshlrev_b32_e32 v0, 11, v6
	v_readlane_b32 s25, v126, 3
	v_readlane_b32 s28, v126, 6
	v_readlane_b32 s29, v126, 7
	v_readlane_b32 s30, v126, 8
	v_readlane_b32 s31, v126, 9
	v_lshl_add_u64 v[84:85], v[4:5], 0, v[0:1]

.Lp0_wdone:
	v_accvgpr_read_b32 v99, a17
	v_accvgpr_read_b32 v97, a15
	v_accvgpr_read_b32 v96, a14
	v_accvgpr_read_b32 v98, a16
	v_pk_mul_f32 v[80:81], v[96:97], v[72:73] op_sel_hi:[1,0]
	ds_write2_b32 v75, v80, v81 offset1:1
	v_pk_mul_f32 v[80:81], v[98:99], v[72:73] op_sel_hi:[1,0]
	v_accvgpr_read_b32 v99, a29
	v_accvgpr_read_b32 v97, a27
	v_accvgpr_read_b32 v96, a26
	ds_write2_b32 v75, v80, v81 offset0:2 offset1:3
	v_accvgpr_read_b32 v98, a28
	v_pk_mul_f32 v[80:81], v[96:97], v[72:73] op_sel_hi:[1,0]
	v_accvgpr_read_b32 v0, a3
	ds_write2_b32 v0, v80, v81 offset1:1
	v_pk_mul_f32 v[80:81], v[98:99], v[72:73] op_sel_hi:[1,0]
	v_accvgpr_read_b32 v99, a39
	v_accvgpr_read_b32 v0, a5
	v_accvgpr_read_b32 v97, a37
	v_accvgpr_read_b32 v96, a36
	ds_write2_b32 v0, v80, v81 offset1:1
	v_accvgpr_read_b32 v98, a38
	v_pk_mul_f32 v[80:81], v[96:97], v[72:73] op_sel_hi:[1,0]
	v_accvgpr_read_b32 v0, a7
	ds_write2_b32 v0, v80, v81 offset1:1
	v_pk_mul_f32 v[80:81], v[98:99], v[72:73] op_sel_hi:[1,0]
	v_accvgpr_read_b32 v99, a49
	v_accvgpr_read_b32 v0, a9
	v_accvgpr_read_b32 v97, a47
	v_accvgpr_read_b32 v96, a46
	ds_write2_b32 v0, v80, v81 offset1:1
	v_accvgpr_read_b32 v98, a48
	v_pk_mul_f32 v[80:81], v[96:97], v[72:73] op_sel_hi:[1,0]
	v_accvgpr_read_b32 v0, a10
	ds_write2_b32 v0, v80, v81 offset1:1
	v_pk_mul_f32 v[80:81], v[98:99], v[72:73] op_sel_hi:[1,0]
	v_accvgpr_read_b32 v99, a55
	v_accvgpr_read_b32 v0, a11
	v_accvgpr_read_b32 v97, a53
	v_accvgpr_read_b32 v96, a52
	ds_write2_b32 v0, v80, v81 offset1:1
	v_accvgpr_read_b32 v98, a54
	v_pk_mul_f32 v[80:81], v[96:97], v[72:73] op_sel_hi:[1,0]
	v_accvgpr_read_b32 v0, a12
	ds_write2_b32 v0, v80, v81 offset1:1
	v_pk_mul_f32 v[80:81], v[98:99], v[72:73] op_sel_hi:[1,0]
	v_accvgpr_read_b32 v99, a59
	v_accvgpr_read_b32 v0, a13
	v_accvgpr_read_b32 v97, a57
	v_accvgpr_read_b32 v96, a56
	ds_write2_b32 v0, v80, v81 offset1:1
	v_accvgpr_read_b32 v98, a58
	v_pk_mul_f32 v[80:81], v[96:97], v[72:73] op_sel_hi:[1,0]
	v_accvgpr_read_b32 v0, a18
	ds_write2_b32 v0, v80, v81 offset1:1
	v_pk_mul_f32 v[80:81], v[98:99], v[72:73] op_sel_hi:[1,0]
	v_accvgpr_read_b32 v99, a63
	v_accvgpr_read_b32 v0, a19
	v_accvgpr_read_b32 v97, a61
	v_accvgpr_read_b32 v96, a60
	ds_write2_b32 v0, v80, v81 offset1:1
	v_accvgpr_read_b32 v98, a62
	v_pk_mul_f32 v[80:81], v[96:97], v[72:73] op_sel_hi:[1,0]
	v_accvgpr_read_b32 v0, a20
	ds_write2_b32 v0, v80, v81 offset1:1
	v_pk_mul_f32 v[80:81], v[98:99], v[72:73] op_sel_hi:[1,0]
	v_accvgpr_read_b32 v99, a67
	v_accvgpr_read_b32 v0, a21
	v_accvgpr_read_b32 v97, a65
	v_accvgpr_read_b32 v96, a64
	ds_write2_b32 v0, v80, v81 offset1:1
	v_accvgpr_read_b32 v98, a66
	v_pk_mul_f32 v[80:81], v[96:97], v[72:73] op_sel_hi:[1,0]
	v_accvgpr_read_b32 v0, a22
	ds_write2_b32 v0, v80, v81 offset1:1
	v_pk_mul_f32 v[80:81], v[98:99], v[72:73] op_sel_hi:[1,0]
	v_accvgpr_read_b32 v99, a71
	v_accvgpr_read_b32 v0, a23
	v_accvgpr_read_b32 v97, a69
	v_accvgpr_read_b32 v96, a68
	ds_write2_b32 v0, v80, v81 offset1:1
	v_accvgpr_read_b32 v98, a70
	v_pk_mul_f32 v[80:81], v[96:97], v[72:73] op_sel_hi:[1,0]
	v_accvgpr_read_b32 v0, a24
	ds_write2_b32 v0, v80, v81 offset1:1
	v_pk_mul_f32 v[80:81], v[98:99], v[72:73] op_sel_hi:[1,0]
	v_accvgpr_read_b32 v99, a75
	v_accvgpr_read_b32 v0, a25
	v_accvgpr_read_b32 v97, a73
	v_accvgpr_read_b32 v96, a72
	ds_write2_b32 v0, v80, v81 offset1:1
	v_accvgpr_read_b32 v98, a74
	v_pk_mul_f32 v[80:81], v[96:97], v[72:73] op_sel_hi:[1,0]
	v_accvgpr_read_b32 v0, a30
	ds_write2_b32 v0, v80, v81 offset1:1
	v_pk_mul_f32 v[80:81], v[98:99], v[72:73] op_sel_hi:[1,0]
	v_accvgpr_read_b32 v0, a31
	ds_write2_b32 v0, v80, v81 offset1:1
	v_pk_mul_f32 v[80:81], v[106:107], v[72:73] op_sel_hi:[1,0]
	v_accvgpr_read_b32 v0, a32
	ds_write2_b32 v0, v80, v81 offset1:1
	v_pk_mul_f32 v[80:81], v[108:109], v[72:73] op_sel_hi:[1,0]
	v_accvgpr_read_b32 v0, a33
	ds_write2_b32 v0, v80, v81 offset1:1
	v_pk_mul_f32 v[80:81], v[110:111], v[72:73] op_sel_hi:[1,0]
	v_accvgpr_read_b32 v0, a34
	ds_write2_b32 v0, v80, v81 offset1:1
	v_pk_mul_f32 v[80:81], v[112:113], v[72:73] op_sel_hi:[1,0]
	v_accvgpr_read_b32 v0, a35
	ds_write2_b32 v0, v80, v81 offset1:1
	v_pk_mul_f32 v[80:81], v[114:115], v[72:73] op_sel_hi:[1,0]
	v_accvgpr_read_b32 v0, a40
	ds_write2_b32 v0, v80, v81 offset1:1
	v_pk_mul_f32 v[80:81], v[116:117], v[72:73] op_sel_hi:[1,0]
	v_accvgpr_read_b32 v0, a41
	ds_write2_b32 v0, v80, v81 offset1:1
	v_pk_mul_f32 v[80:81], v[118:119], v[72:73] op_sel_hi:[1,0]
	v_accvgpr_read_b32 v0, a42
	ds_write2_b32 v0, v80, v81 offset1:1
	v_pk_mul_f32 v[80:81], v[120:121], v[72:73] op_sel_hi:[1,0]
	v_accvgpr_read_b32 v0, a43
	ds_write2_b32 v0, v80, v81 offset1:1
	v_pk_mul_f32 v[80:81], v[122:123], v[72:73] op_sel_hi:[1,0]
	v_accvgpr_read_b32 v0, a44
	ds_write2_b32 v0, v80, v81 offset1:1
	v_pk_mul_f32 v[80:81], v[124:125], v[72:73] op_sel_hi:[1,0]
	v_accvgpr_read_b32 v0, a45
	ds_write2_b32 v0, v80, v81 offset1:1
	v_pk_mul_f32 v[80:81], v[66:67], v[72:73] op_sel_hi:[1,0]
	v_accvgpr_read_b32 v0, a50
	ds_write2_b32 v0, v80, v81 offset1:1
	v_pk_mul_f32 v[80:81], v[68:69], v[72:73] op_sel_hi:[1,0]
	v_accvgpr_read_b32 v0, a51
	ds_write2_b32 v0, v80, v81 offset1:1
	v_add_u32_e32 v0, s80, v91
	v_cmp_gt_i32_e32 vcc, s19, v0
	v_mov_b32_e32 v88, v73
	v_mov_b64_e32 v[80:81], v[78:79]
	s_and_saveexec_b64 s[0:1], vcc
	s_cbranch_execz .LBB0_72
	v_cmp_lt_i32_e32 vcc, s21, v0
	s_and_saveexec_b64 s[12:13], vcc
	s_xor_b64 s[12:13], exec, s[12:13]
	s_cbranch_execz .LBB0_84
	v_lshlrev_b32_e32 v66, 6, v0
	v_add_u32_e32 v0, 0xffff8000, v0
	v_and_b32_e32 v72, 0x3c0, v66
	v_lshlrev_b32_e32 v66, 2, v0
	v_lshrrev_b32_e32 v0, 9, v0
	v_and_b32_e32 v80, 0x7c0, v66
	v_readlane_b32 s24, v126, 2
	v_accvgpr_read_b32 v68, a1
	v_lshlrev_b64 v[66:67], 23, v[0:1]
	v_readlane_b32 s26, v126, 4
	v_readlane_b32 s27, v126, 5
	v_or_b32_e32 v68, v80, v68
	v_lshlrev_b32_e32 v68, 12, v68
	v_lshl_add_u64 v[66:67], s[26:27], 0, v[66:67]
	v_mov_b32_e32 v69, v1
	v_lshl_add_u64 v[66:67], v[66:67], 0, v[68:69]
	v_lshlrev_b32_e32 v68, 2, v72
	v_lshl_add_u64 v[66:67], v[66:67], 0, v[68:69]
	v_lshlrev_b64 v[68:69], 21, v[0:1]
	v_lshl_add_u64 v[68:69], s[8:9], 0, v[68:69]
	v_lshlrev_b32_e32 v0, 11, v72
	v_readlane_b32 s25, v126, 3
	v_readlane_b32 s28, v126, 6
	v_readlane_b32 s29, v126, 7
	v_readlane_b32 s30, v126, 8
	v_readlane_b32 s31, v126, 9
	v_lshl_add_u64 v[84:85], v[68:69], 0, v[0:1]
